# swiglu epilogue stores paced with vmcnt(1) between sections
# speedup vs baseline: 1.0006x; 1.0006x over previous
.LBB0_503:
	v_mov_b32_e32 v139, v174
	s_lshl_b32 s5, s9, 8
	s_add_i32 s5, s5, s70
	v_and_or_b32 v138, v139, 15, s5
	s_lshl_b32 s5, s8, 7
	v_ashrrev_i32_e32 v139, 1, v139
	s_or_b32 s5, s5, s71
	v_and_b32_e32 v139, -8, v139
	v_add_u32_e32 v148, s5, v139
	v_ashrrev_i32_e32 v149, 31, v148
	v_mov_b64_e32 v[146:147], s[0:1]
	v_ashrrev_i32_e32 v139, 31, v138
	v_mad_i64_i32 v[150:151], s[8:9], v138, s73, v[146:147]
	v_lshlrev_b64 v[148:149], 1, v[148:149]
	v_lshl_add_u64 v[152:153], v[150:151], 0, v[148:149]
	v_lshl_add_u64 v[150:151], v[138:139], 2, s[2:3]
	global_load_dword v206, v[150:151], off
	global_load_dword v208, v[150:151], off offset:64
	global_load_dword v210, v[150:151], off offset:128
	global_load_dword v212, v[150:151], off offset:192
	global_load_dword v214, v[150:151], off offset:512
	global_load_dword v216, v[150:151], off offset:576
	global_load_dword v218, v[150:151], off offset:640
	global_load_dword v220, v[150:151], off offset:704
	s_mov_b64 s[42:43], -1
	s_andn2_b64 vcc, exec, s[40:41]
	v_mov_b32_e32 v154, 0xbfb8aa3b
	v_mov_b32_e32 v155, 0xbfb8aa3b
	v_mov_b32_e32 v156, 1.0
	v_mov_b32_e32 v157, 1.0
	v_mov_b32_e32 v159, 0
	s_waitcnt vmcnt(0)
	v_pk_mul_f32 v[128:129], v[128:129], v[206:207] op_sel_hi:[1,0]
	v_pk_mul_f32 v[130:131], v[130:131], v[206:207] op_sel_hi:[1,0]
	v_pk_mul_f32 v[124:125], v[124:125], v[206:207] op_sel_hi:[1,0]
	v_pk_mul_f32 v[126:127], v[126:127], v[206:207] op_sel_hi:[1,0]
	v_pk_mul_f32 v[162:163], v[128:129], v[154:155]
	v_pk_mul_f32 v[164:165], v[130:131], v[154:155]
	v_pk_mul_f32 v[166:167], v[124:125], v[154:155]
	v_pk_mul_f32 v[168:169], v[126:127], v[154:155]
	v_exp_f32_e32 v162, v162
	v_exp_f32_e32 v163, v163
	v_exp_f32_e32 v164, v164
	v_exp_f32_e32 v165, v165
	v_exp_f32_e32 v166, v166
	v_exp_f32_e32 v167, v167
	v_exp_f32_e32 v168, v168
	v_exp_f32_e32 v169, v169
	v_pk_mul_f32 v[120:121], v[120:121], v[206:207] op_sel_hi:[1,0]
	v_pk_mul_f32 v[122:123], v[122:123], v[206:207] op_sel_hi:[1,0]
	v_pk_mul_f32 v[116:117], v[116:117], v[206:207] op_sel_hi:[1,0]
	v_pk_mul_f32 v[118:119], v[118:119], v[206:207] op_sel_hi:[1,0]
	v_pk_add_f32 v[162:163], v[162:163], v[156:157]
	v_pk_add_f32 v[164:165], v[164:165], v[156:157]
	v_pk_add_f32 v[166:167], v[166:167], v[156:157]
	v_pk_add_f32 v[168:169], v[168:169], v[156:157]
	v_rcp_f32_e32 v162, v162
	v_rcp_f32_e32 v163, v163
	v_rcp_f32_e32 v164, v164
	v_rcp_f32_e32 v165, v165
	v_rcp_f32_e32 v166, v166
	v_rcp_f32_e32 v167, v167
	v_rcp_f32_e32 v168, v168
	v_rcp_f32_e32 v169, v169
	v_pk_mul_f32 v[128:129], v[128:129], v[120:121]
	v_pk_mul_f32 v[130:131], v[130:131], v[122:123]
	v_pk_mul_f32 v[124:125], v[124:125], v[116:117]
	v_pk_mul_f32 v[126:127], v[126:127], v[118:119]
	v_pk_mul_f32 v[128:129], v[128:129], v[162:163]
	v_pk_mul_f32 v[130:131], v[130:131], v[164:165]
	v_pk_mul_f32 v[124:125], v[124:125], v[166:167]
	v_pk_mul_f32 v[126:127], v[126:127], v[168:169]
	v_cvt_pk_bf16_f32 v170, v128, v129
	v_cvt_pk_bf16_f32 v171, v130, v131
	v_cvt_pk_bf16_f32 v172, v124, v125
	v_cvt_pk_bf16_f32 v173, v126, v127
	global_store_dwordx4 v[152:153], v[170:173], off
	s_waitcnt vmcnt(1)
	v_pk_mul_f32 v[112:113], v[112:113], v[208:209] op_sel_hi:[1,0]
	v_pk_mul_f32 v[114:115], v[114:115], v[208:209] op_sel_hi:[1,0]
	v_pk_mul_f32 v[108:109], v[108:109], v[208:209] op_sel_hi:[1,0]
	v_pk_mul_f32 v[110:111], v[110:111], v[208:209] op_sel_hi:[1,0]
	v_pk_mul_f32 v[162:163], v[112:113], v[154:155]
	v_pk_mul_f32 v[164:165], v[114:115], v[154:155]
	v_pk_mul_f32 v[166:167], v[108:109], v[154:155]
	v_pk_mul_f32 v[168:169], v[110:111], v[154:155]
	v_exp_f32_e32 v162, v162
	v_exp_f32_e32 v163, v163
	v_exp_f32_e32 v164, v164
	v_exp_f32_e32 v165, v165
	v_exp_f32_e32 v166, v166
	v_exp_f32_e32 v167, v167
	v_exp_f32_e32 v168, v168
	v_exp_f32_e32 v169, v169
	v_pk_mul_f32 v[104:105], v[104:105], v[208:209] op_sel_hi:[1,0]
	v_pk_mul_f32 v[106:107], v[106:107], v[208:209] op_sel_hi:[1,0]
	v_pk_mul_f32 v[100:101], v[100:101], v[208:209] op_sel_hi:[1,0]
	v_pk_mul_f32 v[102:103], v[102:103], v[208:209] op_sel_hi:[1,0]
	v_pk_add_f32 v[162:163], v[162:163], v[156:157]
	v_pk_add_f32 v[164:165], v[164:165], v[156:157]
	v_pk_add_f32 v[166:167], v[166:167], v[156:157]
	v_pk_add_f32 v[168:169], v[168:169], v[156:157]
	v_rcp_f32_e32 v162, v162
	v_rcp_f32_e32 v163, v163
	v_rcp_f32_e32 v164, v164
	v_rcp_f32_e32 v165, v165
	v_rcp_f32_e32 v166, v166
	v_rcp_f32_e32 v167, v167
	v_rcp_f32_e32 v168, v168
	v_rcp_f32_e32 v169, v169
	v_pk_mul_f32 v[112:113], v[112:113], v[104:105]
	v_pk_mul_f32 v[114:115], v[114:115], v[106:107]
	v_pk_mul_f32 v[108:109], v[108:109], v[100:101]
	v_pk_mul_f32 v[110:111], v[110:111], v[102:103]
	v_pk_mul_f32 v[112:113], v[112:113], v[162:163]
	v_pk_mul_f32 v[114:115], v[114:115], v[164:165]
	v_pk_mul_f32 v[108:109], v[108:109], v[166:167]
	v_pk_mul_f32 v[110:111], v[110:111], v[168:169]
	v_cvt_pk_bf16_f32 v186, v112, v113
	v_cvt_pk_bf16_f32 v187, v114, v115
	v_cvt_pk_bf16_f32 v188, v108, v109
	v_cvt_pk_bf16_f32 v189, v110, v111
	v_mov_b32_e32 v158, 0x16000
	v_lshl_add_u64 v[160:161], v[152:153], 0, v[158:159]
	global_store_dwordx4 v[160:161], v[186:189], off
	s_waitcnt vmcnt(1)
	v_pk_mul_f32 v[96:97], v[96:97], v[210:211] op_sel_hi:[1,0]
	v_pk_mul_f32 v[98:99], v[98:99], v[210:211] op_sel_hi:[1,0]
	v_pk_mul_f32 v[92:93], v[92:93], v[210:211] op_sel_hi:[1,0]
	v_pk_mul_f32 v[94:95], v[94:95], v[210:211] op_sel_hi:[1,0]
	v_pk_mul_f32 v[162:163], v[96:97], v[154:155]
	v_pk_mul_f32 v[164:165], v[98:99], v[154:155]
	v_pk_mul_f32 v[166:167], v[92:93], v[154:155]
	v_pk_mul_f32 v[168:169], v[94:95], v[154:155]
	v_exp_f32_e32 v162, v162
	v_exp_f32_e32 v163, v163
	v_exp_f32_e32 v164, v164
	v_exp_f32_e32 v165, v165
	v_exp_f32_e32 v166, v166
	v_exp_f32_e32 v167, v167
	v_exp_f32_e32 v168, v168
	v_exp_f32_e32 v169, v169
	v_pk_mul_f32 v[88:89], v[88:89], v[210:211] op_sel_hi:[1,0]
	v_pk_mul_f32 v[90:91], v[90:91], v[210:211] op_sel_hi:[1,0]
	v_pk_mul_f32 v[84:85], v[84:85], v[210:211] op_sel_hi:[1,0]
	v_pk_mul_f32 v[86:87], v[86:87], v[210:211] op_sel_hi:[1,0]
	v_pk_add_f32 v[162:163], v[162:163], v[156:157]
	v_pk_add_f32 v[164:165], v[164:165], v[156:157]
	v_pk_add_f32 v[166:167], v[166:167], v[156:157]
	v_pk_add_f32 v[168:169], v[168:169], v[156:157]
	v_rcp_f32_e32 v162, v162
	v_rcp_f32_e32 v163, v163
	v_rcp_f32_e32 v164, v164
	v_rcp_f32_e32 v165, v165
	v_rcp_f32_e32 v166, v166
	v_rcp_f32_e32 v167, v167
	v_rcp_f32_e32 v168, v168
	v_rcp_f32_e32 v169, v169
	v_pk_mul_f32 v[96:97], v[96:97], v[88:89]
	v_pk_mul_f32 v[98:99], v[98:99], v[90:91]
	v_pk_mul_f32 v[92:93], v[92:93], v[84:85]
	v_pk_mul_f32 v[94:95], v[94:95], v[86:87]
	v_pk_mul_f32 v[96:97], v[96:97], v[162:163]
	v_pk_mul_f32 v[98:99], v[98:99], v[164:165]
	v_pk_mul_f32 v[92:93], v[92:93], v[166:167]
	v_pk_mul_f32 v[94:95], v[94:95], v[168:169]
	v_cvt_pk_bf16_f32 v170, v96, v97
	v_cvt_pk_bf16_f32 v171, v98, v99
	v_cvt_pk_bf16_f32 v172, v92, v93
	v_cvt_pk_bf16_f32 v173, v94, v95
	v_mov_b32_e32 v158, 0x2c000
	v_lshl_add_u64 v[160:161], v[152:153], 0, v[158:159]
	global_store_dwordx4 v[160:161], v[170:173], off
	s_waitcnt vmcnt(1)
	v_pk_mul_f32 v[80:81], v[80:81], v[212:213] op_sel_hi:[1,0]
	v_pk_mul_f32 v[82:83], v[82:83], v[212:213] op_sel_hi:[1,0]
	v_pk_mul_f32 v[76:77], v[76:77], v[212:213] op_sel_hi:[1,0]
	v_pk_mul_f32 v[78:79], v[78:79], v[212:213] op_sel_hi:[1,0]
	v_pk_mul_f32 v[162:163], v[80:81], v[154:155]
	v_pk_mul_f32 v[164:165], v[82:83], v[154:155]
	v_pk_mul_f32 v[166:167], v[76:77], v[154:155]
	v_pk_mul_f32 v[168:169], v[78:79], v[154:155]
	v_exp_f32_e32 v162, v162
	v_exp_f32_e32 v163, v163
	v_exp_f32_e32 v164, v164
	v_exp_f32_e32 v165, v165
	v_exp_f32_e32 v166, v166
	v_exp_f32_e32 v167, v167
	v_exp_f32_e32 v168, v168
	v_exp_f32_e32 v169, v169
	v_pk_mul_f32 v[72:73], v[72:73], v[212:213] op_sel_hi:[1,0]
	v_pk_mul_f32 v[74:75], v[74:75], v[212:213] op_sel_hi:[1,0]
	v_pk_mul_f32 v[68:69], v[68:69], v[212:213] op_sel_hi:[1,0]
	v_pk_mul_f32 v[70:71], v[70:71], v[212:213] op_sel_hi:[1,0]
	v_pk_add_f32 v[162:163], v[162:163], v[156:157]
	v_pk_add_f32 v[164:165], v[164:165], v[156:157]
	v_pk_add_f32 v[166:167], v[166:167], v[156:157]
	v_pk_add_f32 v[168:169], v[168:169], v[156:157]
	v_rcp_f32_e32 v162, v162
	v_rcp_f32_e32 v163, v163
	v_rcp_f32_e32 v164, v164
	v_rcp_f32_e32 v165, v165
	v_rcp_f32_e32 v166, v166
	v_rcp_f32_e32 v167, v167
	v_rcp_f32_e32 v168, v168
	v_rcp_f32_e32 v169, v169
	v_pk_mul_f32 v[80:81], v[80:81], v[72:73]
	v_pk_mul_f32 v[82:83], v[82:83], v[74:75]
	v_pk_mul_f32 v[76:77], v[76:77], v[68:69]
	v_pk_mul_f32 v[78:79], v[78:79], v[70:71]
	v_pk_mul_f32 v[80:81], v[80:81], v[162:163]
	v_pk_mul_f32 v[82:83], v[82:83], v[164:165]
	v_pk_mul_f32 v[76:77], v[76:77], v[166:167]
	v_pk_mul_f32 v[78:79], v[78:79], v[168:169]
	v_cvt_pk_bf16_f32 v186, v80, v81
	v_cvt_pk_bf16_f32 v187, v82, v83
	v_cvt_pk_bf16_f32 v188, v76, v77
	v_cvt_pk_bf16_f32 v189, v78, v79
	v_mov_b32_e32 v158, 0x42000
	v_lshl_add_u64 v[160:161], v[152:153], 0, v[158:159]
	global_store_dwordx4 v[160:161], v[186:189], off
	s_waitcnt vmcnt(1)
	v_pk_mul_f32 v[64:65], v[64:65], v[214:215] op_sel_hi:[1,0]
	v_pk_mul_f32 v[66:67], v[66:67], v[214:215] op_sel_hi:[1,0]
	v_pk_mul_f32 v[60:61], v[60:61], v[214:215] op_sel_hi:[1,0]
	v_pk_mul_f32 v[62:63], v[62:63], v[214:215] op_sel_hi:[1,0]
	v_pk_mul_f32 v[162:163], v[64:65], v[154:155]
	v_pk_mul_f32 v[164:165], v[66:67], v[154:155]
	v_pk_mul_f32 v[166:167], v[60:61], v[154:155]
	v_pk_mul_f32 v[168:169], v[62:63], v[154:155]
	v_exp_f32_e32 v162, v162
	v_exp_f32_e32 v163, v163
	v_exp_f32_e32 v164, v164
	v_exp_f32_e32 v165, v165
	v_exp_f32_e32 v166, v166
	v_exp_f32_e32 v167, v167
	v_exp_f32_e32 v168, v168
	v_exp_f32_e32 v169, v169
	v_pk_mul_f32 v[56:57], v[56:57], v[214:215] op_sel_hi:[1,0]
	v_pk_mul_f32 v[58:59], v[58:59], v[214:215] op_sel_hi:[1,0]
	v_pk_mul_f32 v[52:53], v[52:53], v[214:215] op_sel_hi:[1,0]
	v_pk_mul_f32 v[54:55], v[54:55], v[214:215] op_sel_hi:[1,0]
	v_pk_add_f32 v[162:163], v[162:163], v[156:157]
	v_pk_add_f32 v[164:165], v[164:165], v[156:157]
	v_pk_add_f32 v[166:167], v[166:167], v[156:157]
	v_pk_add_f32 v[168:169], v[168:169], v[156:157]
	v_rcp_f32_e32 v162, v162
	v_rcp_f32_e32 v163, v163
	v_rcp_f32_e32 v164, v164
	v_rcp_f32_e32 v165, v165
	v_rcp_f32_e32 v166, v166
	v_rcp_f32_e32 v167, v167
	v_rcp_f32_e32 v168, v168
	v_rcp_f32_e32 v169, v169
	v_pk_mul_f32 v[64:65], v[64:65], v[56:57]
	v_pk_mul_f32 v[66:67], v[66:67], v[58:59]
	v_pk_mul_f32 v[60:61], v[60:61], v[52:53]
	v_pk_mul_f32 v[62:63], v[62:63], v[54:55]
	v_pk_mul_f32 v[64:65], v[64:65], v[162:163]
	v_pk_mul_f32 v[66:67], v[66:67], v[164:165]
	v_pk_mul_f32 v[60:61], v[60:61], v[166:167]
	v_pk_mul_f32 v[62:63], v[62:63], v[168:169]
	v_cvt_pk_bf16_f32 v170, v64, v65
	v_cvt_pk_bf16_f32 v171, v66, v67
	v_cvt_pk_bf16_f32 v172, v60, v61
	v_cvt_pk_bf16_f32 v173, v62, v63
	v_mov_b32_e32 v158, 0xb0000
	v_lshl_add_u64 v[160:161], v[152:153], 0, v[158:159]
	global_store_dwordx4 v[160:161], v[170:173], off
	s_waitcnt vmcnt(1)
	v_pk_mul_f32 v[48:49], v[48:49], v[216:217] op_sel_hi:[1,0]
	v_pk_mul_f32 v[50:51], v[50:51], v[216:217] op_sel_hi:[1,0]
	v_pk_mul_f32 v[44:45], v[44:45], v[216:217] op_sel_hi:[1,0]
	v_pk_mul_f32 v[46:47], v[46:47], v[216:217] op_sel_hi:[1,0]
	v_pk_mul_f32 v[162:163], v[48:49], v[154:155]
	v_pk_mul_f32 v[164:165], v[50:51], v[154:155]
	v_pk_mul_f32 v[166:167], v[44:45], v[154:155]
	v_pk_mul_f32 v[168:169], v[46:47], v[154:155]
	v_exp_f32_e32 v162, v162
	v_exp_f32_e32 v163, v163
	v_exp_f32_e32 v164, v164
	v_exp_f32_e32 v165, v165
	v_exp_f32_e32 v166, v166
	v_exp_f32_e32 v167, v167
	v_exp_f32_e32 v168, v168
	v_exp_f32_e32 v169, v169
	v_pk_mul_f32 v[40:41], v[40:41], v[216:217] op_sel_hi:[1,0]
	v_pk_mul_f32 v[42:43], v[42:43], v[216:217] op_sel_hi:[1,0]
	v_pk_mul_f32 v[36:37], v[36:37], v[216:217] op_sel_hi:[1,0]
	v_pk_mul_f32 v[38:39], v[38:39], v[216:217] op_sel_hi:[1,0]
	v_pk_add_f32 v[162:163], v[162:163], v[156:157]
	v_pk_add_f32 v[164:165], v[164:165], v[156:157]
	v_pk_add_f32 v[166:167], v[166:167], v[156:157]
	v_pk_add_f32 v[168:169], v[168:169], v[156:157]
	v_rcp_f32_e32 v162, v162
	v_rcp_f32_e32 v163, v163
	v_rcp_f32_e32 v164, v164
	v_rcp_f32_e32 v165, v165
	v_rcp_f32_e32 v166, v166
	v_rcp_f32_e32 v167, v167
	v_rcp_f32_e32 v168, v168
	v_rcp_f32_e32 v169, v169
	v_pk_mul_f32 v[48:49], v[48:49], v[40:41]
	v_pk_mul_f32 v[50:51], v[50:51], v[42:43]
	v_pk_mul_f32 v[44:45], v[44:45], v[36:37]
	v_pk_mul_f32 v[46:47], v[46:47], v[38:39]
	v_pk_mul_f32 v[48:49], v[48:49], v[162:163]
	v_pk_mul_f32 v[50:51], v[50:51], v[164:165]
	v_pk_mul_f32 v[44:45], v[44:45], v[166:167]
	v_pk_mul_f32 v[46:47], v[46:47], v[168:169]
	v_cvt_pk_bf16_f32 v186, v48, v49
	v_cvt_pk_bf16_f32 v187, v50, v51
	v_cvt_pk_bf16_f32 v188, v44, v45
	v_cvt_pk_bf16_f32 v189, v46, v47
	v_mov_b32_e32 v158, 0xc6000
	v_lshl_add_u64 v[160:161], v[152:153], 0, v[158:159]
	global_store_dwordx4 v[160:161], v[186:189], off
	s_waitcnt vmcnt(1)
	v_pk_mul_f32 v[32:33], v[32:33], v[218:219] op_sel_hi:[1,0]
	v_pk_mul_f32 v[34:35], v[34:35], v[218:219] op_sel_hi:[1,0]
	v_pk_mul_f32 v[28:29], v[28:29], v[218:219] op_sel_hi:[1,0]
	v_pk_mul_f32 v[30:31], v[30:31], v[218:219] op_sel_hi:[1,0]
	v_pk_mul_f32 v[162:163], v[32:33], v[154:155]
	v_pk_mul_f32 v[164:165], v[34:35], v[154:155]
	v_pk_mul_f32 v[166:167], v[28:29], v[154:155]
	v_pk_mul_f32 v[168:169], v[30:31], v[154:155]
	v_exp_f32_e32 v162, v162
	v_exp_f32_e32 v163, v163
	v_exp_f32_e32 v164, v164
	v_exp_f32_e32 v165, v165
	v_exp_f32_e32 v166, v166
	v_exp_f32_e32 v167, v167
	v_exp_f32_e32 v168, v168
	v_exp_f32_e32 v169, v169
	v_pk_mul_f32 v[24:25], v[24:25], v[218:219] op_sel_hi:[1,0]
	v_pk_mul_f32 v[26:27], v[26:27], v[218:219] op_sel_hi:[1,0]
	v_pk_mul_f32 v[20:21], v[20:21], v[218:219] op_sel_hi:[1,0]
	v_pk_mul_f32 v[22:23], v[22:23], v[218:219] op_sel_hi:[1,0]
	v_pk_add_f32 v[162:163], v[162:163], v[156:157]
	v_pk_add_f32 v[164:165], v[164:165], v[156:157]
	v_pk_add_f32 v[166:167], v[166:167], v[156:157]
	v_pk_add_f32 v[168:169], v[168:169], v[156:157]
	v_rcp_f32_e32 v162, v162
	v_rcp_f32_e32 v163, v163
	v_rcp_f32_e32 v164, v164
	v_rcp_f32_e32 v165, v165
	v_rcp_f32_e32 v166, v166
	v_rcp_f32_e32 v167, v167
	v_rcp_f32_e32 v168, v168
	v_rcp_f32_e32 v169, v169
	v_pk_mul_f32 v[32:33], v[32:33], v[24:25]
	v_pk_mul_f32 v[34:35], v[34:35], v[26:27]
	v_pk_mul_f32 v[28:29], v[28:29], v[20:21]
	v_pk_mul_f32 v[30:31], v[30:31], v[22:23]
	v_pk_mul_f32 v[32:33], v[32:33], v[162:163]
	v_pk_mul_f32 v[34:35], v[34:35], v[164:165]
	v_pk_mul_f32 v[28:29], v[28:29], v[166:167]
	v_pk_mul_f32 v[30:31], v[30:31], v[168:169]
	v_cvt_pk_bf16_f32 v170, v32, v33
	v_cvt_pk_bf16_f32 v171, v34, v35
	v_cvt_pk_bf16_f32 v172, v28, v29
	v_cvt_pk_bf16_f32 v173, v30, v31
	v_mov_b32_e32 v158, 0xdc000
	v_lshl_add_u64 v[160:161], v[152:153], 0, v[158:159]
	global_store_dwordx4 v[160:161], v[170:173], off
	s_waitcnt vmcnt(1)
	v_pk_mul_f32 v[16:17], v[16:17], v[220:221] op_sel_hi:[1,0]
	v_pk_mul_f32 v[18:19], v[18:19], v[220:221] op_sel_hi:[1,0]
	v_pk_mul_f32 v[12:13], v[12:13], v[220:221] op_sel_hi:[1,0]
	v_pk_mul_f32 v[14:15], v[14:15], v[220:221] op_sel_hi:[1,0]
	v_pk_mul_f32 v[162:163], v[16:17], v[154:155]
	v_pk_mul_f32 v[164:165], v[18:19], v[154:155]
	v_pk_mul_f32 v[166:167], v[12:13], v[154:155]
	v_pk_mul_f32 v[168:169], v[14:15], v[154:155]
	v_exp_f32_e32 v162, v162
	v_exp_f32_e32 v163, v163
	v_exp_f32_e32 v164, v164
	v_exp_f32_e32 v165, v165
	v_exp_f32_e32 v166, v166
	v_exp_f32_e32 v167, v167
	v_exp_f32_e32 v168, v168
	v_exp_f32_e32 v169, v169
	v_pk_mul_f32 v[8:9], v[8:9], v[220:221] op_sel_hi:[1,0]
	v_pk_mul_f32 v[10:11], v[10:11], v[220:221] op_sel_hi:[1,0]
	v_pk_mul_f32 v[4:5], v[4:5], v[220:221] op_sel_hi:[1,0]
	v_pk_mul_f32 v[6:7], v[6:7], v[220:221] op_sel_hi:[1,0]
	v_pk_add_f32 v[162:163], v[162:163], v[156:157]
	v_pk_add_f32 v[164:165], v[164:165], v[156:157]
	v_pk_add_f32 v[166:167], v[166:167], v[156:157]
	v_pk_add_f32 v[168:169], v[168:169], v[156:157]
	v_rcp_f32_e32 v162, v162
	v_rcp_f32_e32 v163, v163
	v_rcp_f32_e32 v164, v164
	v_rcp_f32_e32 v165, v165
	v_rcp_f32_e32 v166, v166
	v_rcp_f32_e32 v167, v167
	v_rcp_f32_e32 v168, v168
	v_rcp_f32_e32 v169, v169
	v_pk_mul_f32 v[16:17], v[16:17], v[8:9]
	v_pk_mul_f32 v[18:19], v[18:19], v[10:11]
	v_pk_mul_f32 v[12:13], v[12:13], v[4:5]
	v_pk_mul_f32 v[14:15], v[14:15], v[6:7]
	v_pk_mul_f32 v[16:17], v[16:17], v[162:163]
	v_pk_mul_f32 v[18:19], v[18:19], v[164:165]
	v_pk_mul_f32 v[12:13], v[12:13], v[166:167]
	v_pk_mul_f32 v[14:15], v[14:15], v[168:169]
	v_cvt_pk_bf16_f32 v186, v16, v17
	v_cvt_pk_bf16_f32 v187, v18, v19
	v_cvt_pk_bf16_f32 v188, v12, v13
	v_cvt_pk_bf16_f32 v189, v14, v15
	v_mov_b32_e32 v158, 0xf2000
	v_lshl_add_u64 v[160:161], v[152:153], 0, v[158:159]
	global_store_dwordx4 v[160:161], v[186:189], off
	s_cbranch_vccnz .LBB0_496
	s_and_b64 vcc, exec, s[38:39]
	s_cbranch_vccnz .LBB0_495
	s_barrier
	s_branch .LBB0_495
